# attention finalize: 16 gate-tile LDS reads hoisted to the head of the store section (on coalesced asave)
# speedup vs baseline: 1.0129x; 1.0024x over previous
; DI unsigned pack2(float a, float b) { f2_t v = {a, b}; bf2_t r = __builtin_convertvector(v, bf2_t); return __builtin_bit_cast(unsigned, r); }
; DI float bf_lo(unsigned u) { return __uint_as_float(u << 16); }
; DI float bf_hi(unsigned u) { return __uint_as_float(u & 0xffff0000u); }
; template <int PM> DI void attn_phase(const Params& p, int l, char* smem, int* s_item, int wv, int cidx) {
;     ...
;       {
;         const char* gl = gate_s + (w * 32 + l31) * 264 + 8 * h;
;         u16* op = p.O + (size_t)Rq * DM + mixer * 512 + head * 128 + 4 * h;
;         const float* sg = sg_s + 4 * h;
; #pragma unroll
;         for (int db = 0; db < 4; ++db)
; #pragma unroll
;           for (int g = 0; g < 4; ++g) {
;             const int d = db * 32 + 8 * g;
;             f32x4 sv = {1.f, 1.f, 1.f, 1.f};
;             if (mixer == 0) sv = *(const f32x4*)(sg + d);
;             const u32x2 gv = *(const u32x2*)(gl + d * 2);
;             u32x2 o;
;             o[0] = pack2(ov[db][4 * g + 0] * rr * sv[0] * bf_lo(gv[0]), ov[db][4 * g + 1] * rr * sv[1] * bf_hi(gv[0]));
;             o[1] = pack2(ov[db][4 * g + 2] * rr * sv[2] * bf_lo(gv[1]), ov[db][4 * g + 3] * rr * sv[3] * bf_hi(gv[1]));
;             *(u32x2*)(op + d) = o;
;           }
.LBB0_527:
	ds_read_b64 v[16:17], v252
	ds_read_b64 v[18:19], v252 offset:16
	ds_read_b64 v[20:21], v252 offset:32
	ds_read_b64 v[22:23], v252 offset:48
	ds_read_b64 v[24:25], v252 offset:64
	ds_read_b64 v[26:27], v252 offset:80
	ds_read_b64 v[28:29], v252 offset:96
	ds_read_b64 v[30:31], v252 offset:112
	ds_read_b64 v[32:33], v252 offset:128
	ds_read_b64 v[34:35], v252 offset:144
	ds_read_b64 v[36:37], v252 offset:160
	ds_read_b64 v[38:39], v252 offset:176
	ds_read_b64 v[40:41], v252 offset:192
	ds_read_b64 v[42:43], v252 offset:208
	ds_read_b64 v[44:45], v252 offset:224
	ds_read_b64 v[46:47], v252 offset:240
	s_and_b64 vcc, exec, s[72:73]
	v_mov_b32_e32 v93, 1.0
	v_mov_b32_e32 v94, 1.0
	v_mov_b32_e32 v95, 1.0
	s_cbranch_vccnz .LBB0_529
	ds_read_b128 v[92:95], v245
.LBB0_529:
	s_waitcnt lgkmcnt(0)
	v_mov_b64_e32 v[172:173], v[16:17]
	v_pk_mul_f32 v[106:107], v[106:107], v[170:171] op_sel_hi:[1,0]
	v_pk_mul_f32 v[104:105], v[104:105], v[170:171] op_sel_hi:[1,0]
	s_waitcnt lgkmcnt(0)
	v_pk_mul_f32 v[92:93], v[106:107], v[92:93]
	v_pk_mul_f32 v[94:95], v[104:105], v[94:95]
	s_waitcnt lgkmcnt(0)
	v_lshlrev_b32_e32 v106, 16, v172
	v_and_b32_e32 v107, 0xffff0000, v172
	v_lshlrev_b32_e32 v104, 16, v173
	v_and_b32_e32 v105, 0xffff0000, v173
	v_pk_mul_f32 v[92:93], v[92:93], v[106:107]
	v_pk_mul_f32 v[94:95], v[94:95], v[104:105]
	v_cvt_pk_bf16_f32 v92, v92, v93
	v_cvt_pk_bf16_f32 v93, v94, v95
	global_store_dwordx2 v[226:227], v[92:93], off
	v_mov_b32_e32 v92, 1.0
	s_and_b64 vcc, exec, s[72:73]
	v_mov_b32_e32 v104, 1.0
	v_mov_b32_e32 v105, 1.0
	v_mov_b32_e32 v106, 1.0
	v_mov_b32_e32 v107, 1.0
	s_cbranch_vccnz .LBB0_531
	ds_read_b128 v[104:107], v245 offset:32
.LBB0_531:
	v_mov_b64_e32 v[94:95], v[18:19]
	v_mov_b32_e32 v171, v170
	v_pk_mul_f32 v[112:113], v[112:113], v[170:171]
	s_and_b64 vcc, exec, s[72:73]
	s_waitcnt lgkmcnt(0)
	v_pk_mul_f32 v[104:105], v[112:113], v[104:105]
	s_waitcnt lgkmcnt(0)
	v_lshlrev_b32_e32 v112, 16, v94
	v_and_b32_e32 v113, 0xffff0000, v94
	v_pk_mul_f32 v[104:105], v[104:105], v[112:113]
	v_mov_b32_e32 v93, 1.0
	v_cvt_pk_bf16_f32 v94, v104, v105
	v_pk_mul_f32 v[104:105], v[108:109], v[170:171]
	s_nop 0
	v_pk_mul_f32 v[104:105], v[104:105], v[106:107]
	v_lshlrev_b32_e32 v106, 16, v95
	v_and_b32_e32 v107, 0xffff0000, v95
	v_pk_mul_f32 v[104:105], v[104:105], v[106:107]
	s_nop 0
	v_cvt_pk_bf16_f32 v95, v104, v105
	global_store_dwordx2 v[226:227], v[94:95], off offset:16
	v_mov_b32_e32 v94, 1.0
	v_mov_b32_e32 v95, 1.0
	s_cbranch_vccnz .LBB0_533
	ds_read_b128 v[92:95], v245 offset:64
.LBB0_533:
	v_mov_b64_e32 v[104:105], v[20:21]
	v_pk_mul_f32 v[106:107], v[110:111], v[170:171]
	v_pk_mul_f32 v[14:15], v[14:15], v[170:171]
	s_waitcnt lgkmcnt(0)
	v_pk_mul_f32 v[92:93], v[106:107], v[92:93]
	v_pk_mul_f32 v[14:15], v[14:15], v[94:95]
	s_waitcnt lgkmcnt(0)
	v_lshlrev_b32_e32 v106, 16, v104
	v_and_b32_e32 v107, 0xffff0000, v104
	v_lshlrev_b32_e32 v94, 16, v105
	v_and_b32_e32 v95, 0xffff0000, v105
	v_pk_mul_f32 v[92:93], v[92:93], v[106:107]
	v_pk_mul_f32 v[14:15], v[14:15], v[94:95]
	v_cvt_pk_bf16_f32 v92, v92, v93
	v_cvt_pk_bf16_f32 v93, v14, v15
	global_store_dwordx2 v[226:227], v[92:93], off offset:32
	v_mov_b32_e32 v92, 1.0
	s_and_b64 vcc, exec, s[72:73]
	v_mov_b32_e32 v104, 1.0
	v_mov_b32_e32 v105, 1.0
	v_mov_b32_e32 v106, 1.0
	v_mov_b32_e32 v107, 1.0
	s_cbranch_vccnz .LBB0_535
	ds_read_b128 v[104:107], v245 offset:96
.LBB0_535:
	v_mov_b64_e32 v[14:15], v[22:23]
	v_pk_mul_f32 v[94:95], v[114:115], v[170:171]
	v_pk_mul_f32 v[108:109], v[116:117], v[170:171]
	s_waitcnt lgkmcnt(0)
	v_pk_mul_f32 v[94:95], v[94:95], v[104:105]
	s_and_b64 vcc, exec, s[72:73]
	s_waitcnt lgkmcnt(0)
	v_lshlrev_b32_e32 v104, 16, v14
	v_and_b32_e32 v105, 0xffff0000, v14
	v_pk_mul_f32 v[94:95], v[94:95], v[104:105]
	v_lshlrev_b32_e32 v104, 16, v15
	v_cvt_pk_bf16_f32 v14, v94, v95
	v_pk_mul_f32 v[94:95], v[108:109], v[106:107]
	v_and_b32_e32 v105, 0xffff0000, v15
	v_pk_mul_f32 v[94:95], v[94:95], v[104:105]
	v_mov_b32_e32 v93, 1.0
	v_cvt_pk_bf16_f32 v15, v94, v95
	v_mov_b32_e32 v94, 1.0
	v_mov_b32_e32 v95, 1.0
	global_store_dwordx2 v[226:227], v[14:15], off offset:48
	s_cbranch_vccnz .LBB0_537
	ds_read_b128 v[92:95], v245 offset:128
.LBB0_537:
	v_mov_b64_e32 v[14:15], v[24:25]
	v_pk_mul_f32 v[104:105], v[132:133], v[170:171]
	v_pk_mul_f32 v[106:107], v[128:129], v[170:171]
	s_waitcnt lgkmcnt(0)
	v_pk_mul_f32 v[92:93], v[104:105], v[92:93]
	s_and_b64 vcc, exec, s[72:73]
	s_waitcnt lgkmcnt(0)
	v_lshlrev_b32_e32 v104, 16, v14
	v_and_b32_e32 v105, 0xffff0000, v14
	v_pk_mul_f32 v[92:93], v[92:93], v[104:105]
	v_mov_b32_e32 v104, 1.0
	v_cvt_pk_bf16_f32 v14, v92, v93
	v_pk_mul_f32 v[92:93], v[106:107], v[94:95]
	v_lshlrev_b32_e32 v94, 16, v15
	v_and_b32_e32 v95, 0xffff0000, v15
	v_pk_mul_f32 v[92:93], v[92:93], v[94:95]
	v_mov_b32_e32 v105, 1.0
	v_cvt_pk_bf16_f32 v15, v92, v93
	v_mov_b32_e32 v92, 1.0
	v_mov_b32_e32 v106, 1.0
	v_mov_b32_e32 v107, 1.0
	global_store_dwordx2 v[226:227], v[14:15], off offset:64
	s_cbranch_vccnz .LBB0_539
	ds_read_b128 v[104:107], v245 offset:160
.LBB0_539:
	v_mov_b64_e32 v[14:15], v[26:27]
	v_pk_mul_f32 v[94:95], v[124:125], v[170:171]
	v_pk_mul_f32 v[108:109], v[122:123], v[170:171]
	s_waitcnt lgkmcnt(0)
	v_pk_mul_f32 v[94:95], v[94:95], v[104:105]
	s_and_b64 vcc, exec, s[72:73]
	s_waitcnt lgkmcnt(0)
	v_lshlrev_b32_e32 v104, 16, v14
	v_and_b32_e32 v105, 0xffff0000, v14
	v_pk_mul_f32 v[94:95], v[94:95], v[104:105]
	v_lshlrev_b32_e32 v104, 16, v15
	v_cvt_pk_bf16_f32 v14, v94, v95
	v_pk_mul_f32 v[94:95], v[108:109], v[106:107]
	v_and_b32_e32 v105, 0xffff0000, v15
	v_pk_mul_f32 v[94:95], v[94:95], v[104:105]
	v_mov_b32_e32 v93, 1.0
	v_cvt_pk_bf16_f32 v15, v94, v95
	v_mov_b32_e32 v94, 1.0
	v_mov_b32_e32 v95, 1.0
	global_store_dwordx2 v[226:227], v[14:15], off offset:80
	s_cbranch_vccnz .LBB0_541
	ds_read_b128 v[92:95], v245 offset:192
; DI unsigned pack2(float a, float b) { f2_t v = {a, b}; bf2_t r = __builtin_convertvector(v, bf2_t); return __builtin_bit_cast(unsigned, r); }
; DI float bf_lo(unsigned u) { return __uint_as_float(u << 16); }
; DI float bf_hi(unsigned u) { return __uint_as_float(u & 0xffff0000u); }
; template <int PM> DI void attn_phase(const Params& p, int l, char* smem, int* s_item, int wv, int cidx) {
;     ...
;       {
;         const char* gl = gate_s + (w * 32 + l31) * 264 + 8 * h;
;         u16* op = p.O + (size_t)Rq * DM + mixer * 512 + head * 128 + 4 * h;
;         const float* sg = sg_s + 4 * h;
; #pragma unroll
;         for (int db = 0; db < 4; ++db)
; #pragma unroll
;           for (int g = 0; g < 4; ++g) {
;             const int d = db * 32 + 8 * g;
;             f32x4 sv = {1.f, 1.f, 1.f, 1.f};
;             if (mixer == 0) sv = *(const f32x4*)(sg + d);
;             const u32x2 gv = *(const u32x2*)(gl + d * 2);
;             u32x2 o;
;             o[0] = pack2(ov[db][4 * g + 0] * rr * sv[0] * bf_lo(gv[0]), ov[db][4 * g + 1] * rr * sv[1] * bf_hi(gv[0]));
;             o[1] = pack2(ov[db][4 * g + 2] * rr * sv[2] * bf_lo(gv[1]), ov[db][4 * g + 3] * rr * sv[3] * bf_hi(gv[1]));
;             *(u32x2*)(op + d) = o;
;           }
.LBB0_541:
	v_mov_b64_e32 v[14:15], v[28:29]
	v_pk_mul_f32 v[104:105], v[120:121], v[170:171]
	v_pk_mul_f32 v[106:107], v[118:119], v[170:171]
	s_waitcnt lgkmcnt(0)
	v_pk_mul_f32 v[92:93], v[104:105], v[92:93]
	s_and_b64 vcc, exec, s[72:73]
	s_waitcnt lgkmcnt(0)
	v_lshlrev_b32_e32 v104, 16, v14
	v_and_b32_e32 v105, 0xffff0000, v14
	v_pk_mul_f32 v[92:93], v[92:93], v[104:105]
	v_mov_b32_e32 v104, 1.0
	v_cvt_pk_bf16_f32 v14, v92, v93
	v_pk_mul_f32 v[92:93], v[106:107], v[94:95]
	v_lshlrev_b32_e32 v94, 16, v15
	v_and_b32_e32 v95, 0xffff0000, v15
	v_pk_mul_f32 v[92:93], v[92:93], v[94:95]
	v_mov_b32_e32 v105, 1.0
	v_cvt_pk_bf16_f32 v15, v92, v93
	v_mov_b32_e32 v92, 1.0
	v_mov_b32_e32 v106, 1.0
	v_mov_b32_e32 v107, 1.0
	global_store_dwordx2 v[226:227], v[14:15], off offset:96
	s_cbranch_vccnz .LBB0_543
	ds_read_b128 v[104:107], v245 offset:224
.LBB0_543:
	v_mov_b64_e32 v[14:15], v[30:31]
	v_pk_mul_f32 v[94:95], v[126:127], v[170:171]
	v_pk_mul_f32 v[108:109], v[130:131], v[170:171]
	s_waitcnt lgkmcnt(0)
	v_pk_mul_f32 v[94:95], v[94:95], v[104:105]
	s_and_b64 vcc, exec, s[72:73]
	s_waitcnt lgkmcnt(0)
	v_lshlrev_b32_e32 v104, 16, v14
	v_and_b32_e32 v105, 0xffff0000, v14
	v_pk_mul_f32 v[94:95], v[94:95], v[104:105]
	v_lshlrev_b32_e32 v104, 16, v15
	v_cvt_pk_bf16_f32 v14, v94, v95
	v_pk_mul_f32 v[94:95], v[108:109], v[106:107]
	v_and_b32_e32 v105, 0xffff0000, v15
	v_pk_mul_f32 v[94:95], v[94:95], v[104:105]
	v_mov_b32_e32 v93, 1.0
	v_cvt_pk_bf16_f32 v15, v94, v95
	v_mov_b32_e32 v94, 1.0
	v_mov_b32_e32 v95, 1.0
	global_store_dwordx2 v[226:227], v[14:15], off offset:112
	s_cbranch_vccnz .LBB0_545
	ds_read_b128 v[92:95], v245 offset:256
.LBB0_545:
	v_mov_b64_e32 v[14:15], v[32:33]
	v_pk_mul_f32 v[104:105], v[152:153], v[170:171]
	v_pk_mul_f32 v[106:107], v[148:149], v[170:171]
	s_waitcnt lgkmcnt(0)
	v_pk_mul_f32 v[92:93], v[104:105], v[92:93]
	s_and_b64 vcc, exec, s[72:73]
	s_waitcnt lgkmcnt(0)
	v_lshlrev_b32_e32 v104, 16, v14
	v_and_b32_e32 v105, 0xffff0000, v14
	v_pk_mul_f32 v[92:93], v[92:93], v[104:105]
	v_mov_b32_e32 v104, 1.0
	v_cvt_pk_bf16_f32 v14, v92, v93
	v_pk_mul_f32 v[92:93], v[106:107], v[94:95]
	v_lshlrev_b32_e32 v94, 16, v15
	v_and_b32_e32 v95, 0xffff0000, v15
	v_pk_mul_f32 v[92:93], v[92:93], v[94:95]
	v_mov_b32_e32 v105, 1.0
	v_cvt_pk_bf16_f32 v15, v92, v93
	v_mov_b32_e32 v92, 1.0
	v_mov_b32_e32 v106, 1.0
	v_mov_b32_e32 v107, 1.0
	global_store_dwordx2 v[226:227], v[14:15], off offset:128
	s_cbranch_vccnz .LBB0_547
	ds_read_b128 v[104:107], v245 offset:288
.LBB0_547:
	v_mov_b64_e32 v[14:15], v[34:35]
	v_pk_mul_f32 v[94:95], v[140:141], v[170:171]
	v_pk_mul_f32 v[108:109], v[138:139], v[170:171]
	s_waitcnt lgkmcnt(0)
	v_pk_mul_f32 v[94:95], v[94:95], v[104:105]
	s_and_b64 vcc, exec, s[72:73]
	s_waitcnt lgkmcnt(0)
	v_lshlrev_b32_e32 v104, 16, v14
	v_and_b32_e32 v105, 0xffff0000, v14
	v_pk_mul_f32 v[94:95], v[94:95], v[104:105]
	v_lshlrev_b32_e32 v104, 16, v15
	v_cvt_pk_bf16_f32 v14, v94, v95
	v_pk_mul_f32 v[94:95], v[108:109], v[106:107]
	v_and_b32_e32 v105, 0xffff0000, v15
	v_pk_mul_f32 v[94:95], v[94:95], v[104:105]
	v_mov_b32_e32 v93, 1.0
	v_cvt_pk_bf16_f32 v15, v94, v95
	v_mov_b32_e32 v94, 1.0
	v_mov_b32_e32 v95, 1.0
	global_store_dwordx2 v[226:227], v[14:15], off offset:144
	s_cbranch_vccnz .LBB0_549
	ds_read_b128 v[92:95], v245 offset:320
.LBB0_549:
	v_mov_b64_e32 v[14:15], v[36:37]
	v_pk_mul_f32 v[104:105], v[136:137], v[170:171]
	v_pk_mul_f32 v[106:107], v[134:135], v[170:171]
	s_waitcnt lgkmcnt(0)
	v_pk_mul_f32 v[92:93], v[104:105], v[92:93]
	s_and_b64 vcc, exec, s[72:73]
	s_waitcnt lgkmcnt(0)
	v_lshlrev_b32_e32 v104, 16, v14
	v_and_b32_e32 v105, 0xffff0000, v14
	v_pk_mul_f32 v[92:93], v[92:93], v[104:105]
	v_mov_b32_e32 v104, 1.0
	v_cvt_pk_bf16_f32 v14, v92, v93
	v_pk_mul_f32 v[92:93], v[106:107], v[94:95]
	v_lshlrev_b32_e32 v94, 16, v15
	v_and_b32_e32 v95, 0xffff0000, v15
	v_pk_mul_f32 v[92:93], v[92:93], v[94:95]
	v_mov_b32_e32 v105, 1.0
	v_cvt_pk_bf16_f32 v15, v92, v93
	v_mov_b32_e32 v92, 1.0
	v_mov_b32_e32 v106, 1.0
	v_mov_b32_e32 v107, 1.0
	global_store_dwordx2 v[226:227], v[14:15], off offset:160
	s_cbranch_vccnz .LBB0_551
	ds_read_b128 v[104:107], v245 offset:352
; DI unsigned pack2(float a, float b) { f2_t v = {a, b}; bf2_t r = __builtin_convertvector(v, bf2_t); return __builtin_bit_cast(unsigned, r); }
; DI float bf_lo(unsigned u) { return __uint_as_float(u << 16); }
; DI float bf_hi(unsigned u) { return __uint_as_float(u & 0xffff0000u); }
; template <int PM> DI void attn_phase(const Params& p, int l, char* smem, int* s_item, int wv, int cidx) {
;     ...
;       {
;         const char* gl = gate_s + (w * 32 + l31) * 264 + 8 * h;
;         u16* op = p.O + (size_t)Rq * DM + mixer * 512 + head * 128 + 4 * h;
;         const float* sg = sg_s + 4 * h;
; #pragma unroll
;         for (int db = 0; db < 4; ++db)
; #pragma unroll
;           for (int g = 0; g < 4; ++g) {
;             const int d = db * 32 + 8 * g;
;             f32x4 sv = {1.f, 1.f, 1.f, 1.f};
;             if (mixer == 0) sv = *(const f32x4*)(sg + d);
;             const u32x2 gv = *(const u32x2*)(gl + d * 2);
;             u32x2 o;
;             o[0] = pack2(ov[db][4 * g + 0] * rr * sv[0] * bf_lo(gv[0]), ov[db][4 * g + 1] * rr * sv[1] * bf_hi(gv[0]));
;             o[1] = pack2(ov[db][4 * g + 2] * rr * sv[2] * bf_lo(gv[1]), ov[db][4 * g + 3] * rr * sv[3] * bf_hi(gv[1]));
;             *(u32x2*)(op + d) = o;
;           }
.LBB0_551:
	v_mov_b64_e32 v[14:15], v[38:39]
	v_pk_mul_f32 v[94:95], v[142:143], v[170:171]
	v_pk_mul_f32 v[108:109], v[150:151], v[170:171]
	s_waitcnt lgkmcnt(0)
	v_pk_mul_f32 v[94:95], v[94:95], v[104:105]
	s_and_b64 vcc, exec, s[72:73]
	s_waitcnt lgkmcnt(0)
	v_lshlrev_b32_e32 v104, 16, v14
	v_and_b32_e32 v105, 0xffff0000, v14
	v_pk_mul_f32 v[94:95], v[94:95], v[104:105]
	v_lshlrev_b32_e32 v104, 16, v15
	v_cvt_pk_bf16_f32 v14, v94, v95
	v_pk_mul_f32 v[94:95], v[108:109], v[106:107]
	v_and_b32_e32 v105, 0xffff0000, v15
	v_pk_mul_f32 v[94:95], v[94:95], v[104:105]
	v_mov_b32_e32 v93, 1.0
	v_cvt_pk_bf16_f32 v15, v94, v95
	v_mov_b32_e32 v94, 1.0
	v_mov_b32_e32 v95, 1.0
	global_store_dwordx2 v[226:227], v[14:15], off offset:176
	s_cbranch_vccnz .LBB0_553
	ds_read_b128 v[92:95], v245 offset:384
.LBB0_553:
	v_mov_b64_e32 v[14:15], v[40:41]
	v_pk_mul_f32 v[104:105], v[168:169], v[170:171]
	v_pk_mul_f32 v[106:107], v[164:165], v[170:171]
	s_waitcnt lgkmcnt(0)
	v_pk_mul_f32 v[92:93], v[104:105], v[92:93]
	s_and_b64 vcc, exec, s[72:73]
	s_waitcnt lgkmcnt(0)
	v_lshlrev_b32_e32 v104, 16, v14
	v_and_b32_e32 v105, 0xffff0000, v14
	v_pk_mul_f32 v[92:93], v[92:93], v[104:105]
	v_mov_b32_e32 v104, 1.0
	v_cvt_pk_bf16_f32 v14, v92, v93
	v_pk_mul_f32 v[92:93], v[106:107], v[94:95]
	v_lshlrev_b32_e32 v94, 16, v15
	v_and_b32_e32 v95, 0xffff0000, v15
	v_pk_mul_f32 v[92:93], v[92:93], v[94:95]
	v_mov_b32_e32 v105, 1.0
	v_cvt_pk_bf16_f32 v15, v92, v93
	v_mov_b32_e32 v92, 1.0
	v_mov_b32_e32 v106, 1.0
	v_mov_b32_e32 v107, 1.0
	global_store_dwordx2 v[226:227], v[14:15], off offset:192
	s_cbranch_vccnz .LBB0_555
	ds_read_b128 v[104:107], v245 offset:416
.LBB0_555:
	v_mov_b64_e32 v[14:15], v[42:43]
	v_pk_mul_f32 v[94:95], v[160:161], v[170:171]
	v_pk_mul_f32 v[108:109], v[158:159], v[170:171]
	s_waitcnt lgkmcnt(0)
	v_pk_mul_f32 v[94:95], v[94:95], v[104:105]
	s_and_b64 vcc, exec, s[72:73]
	s_waitcnt lgkmcnt(0)
	v_lshlrev_b32_e32 v104, 16, v14
	v_and_b32_e32 v105, 0xffff0000, v14
	v_pk_mul_f32 v[94:95], v[94:95], v[104:105]
	v_lshlrev_b32_e32 v104, 16, v15
	v_cvt_pk_bf16_f32 v14, v94, v95
	v_pk_mul_f32 v[94:95], v[108:109], v[106:107]
	v_and_b32_e32 v105, 0xffff0000, v15
	v_pk_mul_f32 v[94:95], v[94:95], v[104:105]
	v_mov_b32_e32 v93, 1.0
	v_cvt_pk_bf16_f32 v15, v94, v95
	v_mov_b32_e32 v94, 1.0
	v_mov_b32_e32 v95, 1.0
	global_store_dwordx2 v[226:227], v[14:15], off offset:208
	s_cbranch_vccnz .LBB0_557
	ds_read_b128 v[92:95], v245 offset:448
.LBB0_557:
	v_mov_b64_e32 v[14:15], v[44:45]
	v_pk_mul_f32 v[104:105], v[156:157], v[170:171]
	v_pk_mul_f32 v[106:107], v[154:155], v[170:171]
	s_waitcnt lgkmcnt(0)
	v_pk_mul_f32 v[92:93], v[104:105], v[92:93]
	s_and_b64 vcc, exec, s[72:73]
	s_waitcnt lgkmcnt(0)
	v_lshlrev_b32_e32 v104, 16, v14
	v_and_b32_e32 v105, 0xffff0000, v14
	v_pk_mul_f32 v[92:93], v[92:93], v[104:105]
	s_nop 0
	v_cvt_pk_bf16_f32 v14, v92, v93
	v_pk_mul_f32 v[92:93], v[106:107], v[94:95]
	v_lshlrev_b32_e32 v94, 16, v15
	v_and_b32_e32 v95, 0xffff0000, v15
	v_pk_mul_f32 v[92:93], v[92:93], v[94:95]
	v_mov_b32_e32 v94, 1.0
	v_cvt_pk_bf16_f32 v15, v92, v93
	v_mov_b32_e32 v92, 1.0
	v_mov_b32_e32 v93, 1.0
	v_mov_b32_e32 v95, 1.0
	global_store_dwordx2 v[226:227], v[14:15], off offset:224
	s_cbranch_vccnz .LBB0_559
	ds_read_b128 v[92:95], v245 offset:480
.LBB0_559:
	v_mov_b64_e32 v[14:15], v[46:47]
	v_pk_mul_f32 v[104:105], v[162:163], v[170:171]
	v_pk_mul_f32 v[106:107], v[166:167], v[170:171]
	s_waitcnt lgkmcnt(0)
	v_pk_mul_f32 v[92:93], v[104:105], v[92:93]
	s_waitcnt lgkmcnt(0)
	v_lshlrev_b32_e32 v104, 16, v14
	v_and_b32_e32 v105, 0xffff0000, v14
	v_pk_mul_f32 v[92:93], v[92:93], v[104:105]
	s_nop 0
	v_cvt_pk_bf16_f32 v14, v92, v93
	v_pk_mul_f32 v[92:93], v[106:107], v[94:95]
	v_lshlrev_b32_e32 v94, 16, v15
	v_and_b32_e32 v95, 0xffff0000, v15
	v_pk_mul_f32 v[92:93], v[92:93], v[94:95]
	s_nop 0
	v_cvt_pk_bf16_f32 v15, v92, v93
	global_store_dwordx2 v[226:227], v[14:15], off offset:240
	s_branch .LBB0_408
